# v5 + phase 10 tile mapping changed to 4 M-tiles x 8 N-tiles per XCD step (each ACT row tile streamed once instead of twice)
# baseline (speedup 1.0000x reference)
; template <class Epi, class Sched, bool SP2 = PG8_SP2>
; __device__ __forceinline__ void gemm_phase(LAS unsigned char* lds, const Gemm g, const Sched& S, const Epi& E) {
;     const int tid = threadIdx.x, wid = __builtin_amdgcn_readfirstlane(tid >> 6), lane = tid & 63, wr = wid >> 2, wc = wid & 3, fr = lane & 15, fq = lane >> 4;
;     const int K = g.K, nt = K / BK, lda = g.lda;
;     unsigned voffA[2], voffB[2];
; #pragma unroll
;     for (int i = 0; i < 2; ++i) { int R, C; stage_rc(tid * 16 + i * 8192, R, C); const int Rb = Epi::PERM ? ((R & ~31) + perm32(R & 31)) : R;
;         voffA[i] = (unsigned)(R * lda + C) * 2u; voffB[i] = (unsigned)(Rb * K + C) * 2u; }
;     const size_t kstep = (size_t)(BK * 2);
;     const size_t hstepA = (size_t)HALF * lda * 2, hstepB = (size_t)HALF * K * 2;
;     const size_t tstepA = 2 * hstepA, tstepB = 2 * hstepB;
;     const unsigned ldsw = (unsigned)wid * 1024u;
;     const int aoff = lds_byte(wr * 64 + fr, fq * 8), boff = lds_byte(wc * 32 + fr, fq * 8);
;     ...
;     Unit cur, nxt; int ui = 0;
;     if (!S.next(0, cur)) return;
;     f32x4 acc[2][2][4][2];
; #pragma unroll
;     for (int a = 0; a < 2; ++a)
; #pragma unroll
;         for (int b = 0; b < 2; ++b)
; #pragma unroll
;             for (int m = 0; m < 4; ++m)
; #pragma unroll
;                 for (int n = 0; n < 2; ++n) acc[a][b][m][n] = (f32x4){0.f, 0.f, 0.f, 0.f};
;     bf16x8 At[4][2], B0[2][2], B1[2][2];
;     const char* cA = (const char*)g.A + (size_t)cur.pm * tstepA; const char* cB = (const char*)g.Bt + (size_t)cur.pn * tstepB;
;     if constexpr (SP2) {
;     PG8_STAGE(PG8_SB(0, 0), cB, voffB); PG8_STAGE(PG8_SB(0, 1), cB + hstepB, voffB); PG8_STAGE(PG8_SA(0, 0), cA, voffA); PG8_STAGE(PG8_SA(0, 1), cA + hstepA, voffA);
;     if (wr == 1) PG8_BAR;
;     PG8_WAIT_V(2); PG8_BAR;
;     PG8_STAGE(PG8_SB(1, 0), cB + kstep, voffB); PG8_STAGE(PG8_SA(1, 0), cA + kstep, voffA); PG8_STAGE(PG8_SB(1, 1), cB + hstepB + kstep, voffB);
;     PG8_WAIT_V(6); PG8_BAR;
;     } else {
;     PG8_STAGE(PG8_SB(0, 0), cB, voffB); PG8_STAGE(PG8_SA(0, 0), cA, voffA); PG8_STAGE(PG8_SB(0, 1), cB + hstepB, voffB); PG8_STAGE(PG8_SA(0, 1), cA + hstepA, voffA);
;     if (wr == 1) PG8_BAR;
;     PG8_WAIT_V(4); PG8_BAR;
;     PG8_STAGE(PG8_SB(1, 0), cB + kstep, voffB); PG8_STAGE(PG8_SA(1, 0), cA + kstep, voffA); PG8_STAGE(PG8_SB(1, 1), cB + hstepB + kstep, voffB);
;     PG8_WAIT_V(6); PG8_BAR;
.LBB0_1074:
	s_waitcnt lgkmcnt(0)
	s_add_u32 s31, s10, 0x26000000
	s_addc_u32 s33, s11, 0
	s_add_u32 s34, s10, 0x4600000
	s_addc_u32 s35, s11, 0
	s_add_i32 s1, s4, s1
	s_addk_i32 s1, 0x60
	s_ashr_i32 s4, s1, 31
	s_lshr_b32 s4, s4, 26
	s_add_i32 s4, s1, s4
	s_ashr_i32 s5, s4, 6
	s_and_b32 s4, s4, 0xffc0
	s_sub_i32 s4, s1, s4
	s_bfe_i32 s1, s4, 0x80000
	s_bfe_u32 s1, s1, 0x3000c
	s_add_i32 s6, s4, s1
	v_lshlrev_b32_e32 v0, 4, v222
	v_and_b32_e32 v1, 32, v222
	s_bfe_i32 s1, s6, 0x80000
	s_and_b32 s6, s6, 0xf8
	v_bfe_u32 v2, v222, 2, 4
	v_bitop3_b32 v8, v0, v1, 48 bitop3:0x6c
	v_lshrrev_b32_e32 v3, 3, v222
	s_movk_i32 s3, 0x70
	v_add_u32_e32 v0, 0x2000, v0
	s_sub_i32 s4, s4, s6
	v_and_or_b32 v3, v3, s3, v2
	v_lshrrev_b32_e32 v0, 7, v0
	s_movk_i32 s3, 0xf0
	s_lshl_b32 s5, s5, 3
	s_sext_i32_i16 s7, s1
	s_sext_i32_i8 s4, s4
	v_and_or_b32 v0, v0, s3, v2
	s_lshr_b32 s3, s2, 6
	s_add_i32 s53, s5, s4
	s_lshr_b32 s6, s53, 2
	s_lshr_b32 s4, s7, 5
	s_xor_b32 s6, s6, s4
	s_and_b32 s6, s6, 1
	s_lshl_b32 s4, s6, 2
	s_xor_b32 s53, s53, s4
	s_lshl_b32 s4, s6, 5
	s_xor_b32 s7, s7, s4
	s_ashr_i32 s4, s7, 3
	s_lshr_b32 s0, s2, 8
	s_lshl_b32 s36, s3, 10
	s_lshr_b32 s1, s7, 3
	s_mul_hi_i32 s5, s4, 0x2c0000
	s_mul_i32 s4, s4, 0x2c0000
	v_and_b32_e32 v9, 64, v222
	s_add_u32 s26, s34, s4
	v_or_b32_e32 v1, v8, v9
	v_mul_u32_u24_e32 v10, 0x2c00, v3
	s_addc_u32 s27, s35, s5
	s_add_i32 s37, s36, 0
	s_waitcnt vmcnt(0)
	v_or_b32_e32 v128, v10, v1
	s_add_i32 m0, s37, 0x10000
	v_mul_u32_u24_e32 v11, 0x2c00, v0
	global_load_lds_dwordx4 v128, s[26:27]
	s_add_i32 m0, s37, 0x12000
	v_or_b32_e32 v130, v11, v1
	s_add_u32 s4, s26, 0x160000
	global_load_lds_dwordx4 v130, s[26:27]
	s_addc_u32 s5, s27, 0
	s_add_i32 m0, s37, 0x14000
	s_mul_i32 s10, s53, 0x2c0000
	global_load_lds_dwordx4 v128, s[4:5]
	s_add_i32 m0, s37, 0x16000
	s_mul_hi_i32 s6, s53, 0x2c0000
	s_add_u32 s24, s31, s10
	s_addc_u32 s25, s33, s6
	s_add_i32 s38, s37, 0x2000
	global_load_lds_dwordx4 v130, s[4:5]
	s_mov_b32 m0, s37
	s_add_u32 s4, s24, 0x160000
	global_load_lds_dwordx4 v128, s[24:25]
	s_mov_b32 m0, s38
	s_addc_u32 s5, s25, 0
	s_add_i32 s39, s37, 0x4000
	global_load_lds_dwordx4 v130, s[24:25]
	s_mov_b32 m0, s39
	s_add_i32 s40, s37, 0x6000
	global_load_lds_dwordx4 v128, s[4:5]
	s_mov_b32 m0, s40
	v_mov_b32_e32 v129, 0
	global_load_lds_dwordx4 v130, s[4:5]
	v_mov_b32_e32 v131, v129
	s_cmp_eq_u32 s0, 1
	s_mov_b32 s41, 0
	v_lshl_add_u64 v[6:7], s[26:27], 0, v[128:129]
	v_lshl_add_u64 v[4:5], s[26:27], 0, v[130:131]
	s_mov_b64 s[6:7], 0x160000
	v_lshl_add_u64 v[0:1], s[24:25], 0, v[128:129]
	s_cselect_b64 s[10:11], -1, 0
	s_cmp_lg_u32 s0, 1
	v_lshl_add_u64 v[2:3], s[24:25], 0, v[130:131]
	s_cbranch_scc1 .LBB0_1076
	s_barrier

;     __device__ bool next(int i, Unit& u) const {
;         const long L = (long)i * G + c; if (L >= nwg) return false;
;         int wgid = (int)L; { const int q = nwg / NXCD, r = nwg % NXCD, xcd = wgid % NXCD, off = wgid / NXCD; wgid = (xcd < r ? xcd * (q + 1) : r * (q + 1) + (xcd - r) * q) + off; }
;         const int nig = WGM * nN, gid = wgid / nig, fm = gid * WGM, gsz = (nM - fm) < WGM ? (nM - fm) : WGM;
;         u.pm = fm + ((wgid % nig) % gsz); u.pn = (wgid % nig) / gsz; return true;
;     }
.LBB0_1084:
	s_ashr_i32 s0, s2, 3
	s_add_i32 s0, s22, s0
	s_ashr_i32 s1, s0, 31
	s_lshr_b32 s1, s1, 26
	s_add_i32 s1, s0, s1
	s_ashr_i32 s2, s1, 6
	s_lshl_b32 s2, s2, 3
	s_sub_i32 s3, 0x80, s2
	s_min_i32 s3, s3, 8
	s_abs_i32 s22, s3
	v_cvt_f32_u32_e32 v0, s22
	s_sub_i32 s28, 0, s22
	s_andn2_b32 s1, s1, 63
	s_sub_i32 s0, s0, s1
	v_rcp_iflag_f32_e32 v0, v0
	s_abs_i32 s1, s0
	s_xor_b32 s23, s0, s3
	s_ashr_i32 s23, s23, 31
	v_mul_f32_e32 v0, 0x4f7ffffe, v0
	v_cvt_u32_f32_e32 v0, v0
	s_nop 0
	v_readfirstlane_b32 s29, v0
	s_mul_i32 s28, s28, s29
	s_mul_hi_u32 s28, s29, s28
	s_add_i32 s29, s29, s28
	s_mul_hi_u32 s28, s1, s29
	s_mul_i32 s29, s28, s22
	s_sub_i32 s1, s1, s29
	s_add_i32 s51, s28, 1
	s_sub_i32 s29, s1, s22
	s_cmp_ge_u32 s1, s22
	s_cselect_b32 s28, s51, s28
	s_cselect_b32 s1, s29, s1
	s_add_i32 s29, s28, 1
	s_cmp_ge_u32 s1, s22
	s_cselect_b32 s1, s29, s28
	s_xor_b32 s1, s1, s23
	s_sub_i32 s51, s1, s23
	s_mul_i32 s1, s51, s3
	s_sub_i32 s0, s0, s1
	s_add_i32 s52, s2, s0
	s_xor_b32 s0, s52, s51
	s_and_b32 s0, s0, 4
	s_xor_b32 s52, s52, s0
	s_xor_b32 s51, s51, s0
